# v38 (staging loads at QK^T slots 4/12/20/28) + relu^2 epilogues without the canonicalising v_max
# speedup vs baseline: 1.0059x; 1.0050x over previous
; __device__ __forceinline__ unsigned cvt_pk_bf16(float lo, float hi) { unsigned r; asm volatile("v_cvt_pk_bf16_f32 %0, %1, %2" : "=v"(r) : "v"(lo), "v"(hi)); return r; }
;     __device__ __forceinline__ void operator()(const f32x4 (&acc)[2][2][4][2], const Unit& u, int wr, int wc, int fr, int fq) const {
;     ...
;         for (int ai = 0; ai < 2; ++ai)
; #pragma unroll
;             for (int m = 0; m < 4; ++m) { bf16_t* rowp = O + (size_t)(row0 + ai * HALF + m * 16) * ldc + col0;
; #pragma unroll
;                 for (int bj = 0; bj < 2; ++bj) { f32x4 v0 = acc[ai][bj][m][0], v1 = acc[ai][bj][m][1];
;                     if (ACT == 1) { v0 = __builtin_elementwise_max(v0, (f32x4){0.f, 0.f, 0.f, 0.f}); v1 = __builtin_elementwise_max(v1, (f32x4){0.f, 0.f, 0.f, 0.f}); v0 = v0 * v0; v1 = v1 * v1; }
;                     if (ACT == 2) { v0 = v0 * sv[bj][0]; v1 = v1 * sv[bj][1]; }
;                     u32x4 w; w.x = cvt_pk_bf16(v0[0], v0[1]); w.y = cvt_pk_bf16(v0[2], v0[3]); w.z = cvt_pk_bf16(v1[0], v1[1]); w.w = cvt_pk_bf16(v1[2], v1[3]);
;                     *(u32x4*)(rowp + bj * HALF) = w; } }
.LBB0_381:
	v_lshl_add_u32 v148, s68, 8, v1
	v_lshl_or_b32 v146, s15, 8, v153
	v_ashrrev_i32_e32 v149, 31, v148
	v_ashrrev_i32_e32 v147, 31, v146
	v_lshlrev_b64 v[150:151], 13, v[148:149]
	v_lshl_add_u64 v[158:159], s[20:21], 0, v[150:151]
	v_lshlrev_b64 v[150:151], 1, v[146:147]
	v_max_f32_e32 v127, 0, v127
	v_max_f32_e32 v126, 0, v126
	v_max_f32_e32 v129, 0, v129
	v_max_f32_e32 v128, 0, v128
	v_max_f32_e32 v123, 0, v123
	v_max_f32_e32 v122, 0, v122
	v_max_f32_e32 v125, 0, v125
	v_max_f32_e32 v124, 0, v124
	v_lshl_add_u64 v[146:147], v[158:159], 0, v[150:151]
	v_pk_mul_f32 v[128:129], v[128:129], v[128:129]
	v_pk_mul_f32 v[126:127], v[126:127], v[126:127]
	v_pk_mul_f32 v[158:159], v[124:125], v[124:125]
	v_pk_mul_f32 v[124:125], v[122:123], v[122:123]
	v_cvt_pk_bf16_f32 v122, v126, v127
	v_cvt_pk_bf16_f32 v123, v128, v129
	v_max_f32_e32 v119, 0, v119
	v_max_f32_e32 v118, 0, v118
	v_max_f32_e32 v115, 0, v115
	v_max_f32_e32 v114, 0, v114
	v_max_f32_e32 v117, 0, v117
	v_max_f32_e32 v116, 0, v116
	v_cvt_pk_bf16_f32 v124, v124, v125
	v_cvt_pk_bf16_f32 v125, v158, v159
	global_store_dwordx4 v[146:147], v[122:125], off
	s_nop 1
	v_max_f32_e32 v121, 0, v121
	v_max_f32_e32 v120, 0, v120
	v_pk_mul_f32 v[118:119], v[118:119], v[118:119]
	v_pk_mul_f32 v[122:123], v[116:117], v[116:117]
	v_pk_mul_f32 v[116:117], v[114:115], v[114:115]
	v_cvt_pk_bf16_f32 v114, v118, v119
	v_pk_mul_f32 v[120:121], v[120:121], v[120:121]
	v_cvt_pk_bf16_f32 v115, v120, v121
	v_cvt_pk_bf16_f32 v116, v116, v117
	v_cvt_pk_bf16_f32 v117, v122, v123
	global_store_dwordx4 v[146:147], v[114:117], off offset:256
	s_nop 1
	v_or_b32_e32 v114, 16, v148
	v_ashrrev_i32_e32 v115, 31, v114
	v_lshlrev_b64 v[114:115], 13, v[114:115]
	v_lshl_add_u64 v[114:115], s[20:21], 0, v[114:115]
	v_max_f32_e32 v111, 0, v111
	v_max_f32_e32 v110, 0, v110
	v_max_f32_e32 v113, 0, v113
	v_max_f32_e32 v112, 0, v112
	v_max_f32_e32 v107, 0, v107
	v_max_f32_e32 v106, 0, v106
	v_max_f32_e32 v109, 0, v109
	v_max_f32_e32 v108, 0, v108
	v_lshl_add_u64 v[114:115], v[114:115], 0, v[150:151]
	v_pk_mul_f32 v[112:113], v[112:113], v[112:113]
	v_pk_mul_f32 v[110:111], v[110:111], v[110:111]
	v_pk_mul_f32 v[116:117], v[108:109], v[108:109]
	v_pk_mul_f32 v[108:109], v[106:107], v[106:107]
	v_cvt_pk_bf16_f32 v106, v110, v111
	v_cvt_pk_bf16_f32 v107, v112, v113
	v_max_f32_e32 v103, 0, v103
	v_max_f32_e32 v102, 0, v102
	v_max_f32_e32 v99, 0, v99
	v_max_f32_e32 v98, 0, v98
	v_max_f32_e32 v101, 0, v101
	v_max_f32_e32 v100, 0, v100
	v_cvt_pk_bf16_f32 v108, v108, v109
	v_cvt_pk_bf16_f32 v109, v116, v117
	global_store_dwordx4 v[114:115], v[106:109], off
	s_nop 1
	v_max_f32_e32 v105, 0, v105
	v_max_f32_e32 v104, 0, v104
	v_pk_mul_f32 v[102:103], v[102:103], v[102:103]
	v_pk_mul_f32 v[106:107], v[100:101], v[100:101]
	v_pk_mul_f32 v[100:101], v[98:99], v[98:99]
	v_cvt_pk_bf16_f32 v98, v102, v103
	v_pk_mul_f32 v[104:105], v[104:105], v[104:105]
	v_cvt_pk_bf16_f32 v99, v104, v105
	v_cvt_pk_bf16_f32 v100, v100, v101
	v_cvt_pk_bf16_f32 v101, v106, v107
	global_store_dwordx4 v[114:115], v[98:101], off offset:256
	s_nop 1
	v_or_b32_e32 v98, 32, v148
	v_ashrrev_i32_e32 v99, 31, v98
	v_lshlrev_b64 v[98:99], 13, v[98:99]
	v_lshl_add_u64 v[98:99], s[20:21], 0, v[98:99]
	v_max_f32_e32 v95, 0, v95
	v_max_f32_e32 v94, 0, v94
	v_max_f32_e32 v97, 0, v97
	v_max_f32_e32 v96, 0, v96
	v_max_f32_e32 v91, 0, v91
	v_max_f32_e32 v90, 0, v90
	v_max_f32_e32 v93, 0, v93
	v_max_f32_e32 v92, 0, v92
	v_lshl_add_u64 v[98:99], v[98:99], 0, v[150:151]
	v_pk_mul_f32 v[96:97], v[96:97], v[96:97]
	v_pk_mul_f32 v[94:95], v[94:95], v[94:95]
	v_pk_mul_f32 v[100:101], v[92:93], v[92:93]
	v_pk_mul_f32 v[92:93], v[90:91], v[90:91]
	v_cvt_pk_bf16_f32 v90, v94, v95
	v_cvt_pk_bf16_f32 v91, v96, v97
	v_max_f32_e32 v87, 0, v87
	v_max_f32_e32 v86, 0, v86
	v_max_f32_e32 v83, 0, v83
	v_max_f32_e32 v82, 0, v82
	v_max_f32_e32 v85, 0, v85
	v_max_f32_e32 v84, 0, v84
	v_cvt_pk_bf16_f32 v92, v92, v93
	v_cvt_pk_bf16_f32 v93, v100, v101
	global_store_dwordx4 v[98:99], v[90:93], off
	s_nop 1
	v_max_f32_e32 v89, 0, v89
	v_max_f32_e32 v88, 0, v88
	v_pk_mul_f32 v[86:87], v[86:87], v[86:87]
	v_pk_mul_f32 v[90:91], v[84:85], v[84:85]
	v_pk_mul_f32 v[84:85], v[82:83], v[82:83]
	v_cvt_pk_bf16_f32 v82, v86, v87
	v_pk_mul_f32 v[88:89], v[88:89], v[88:89]
	v_cvt_pk_bf16_f32 v83, v88, v89
	v_cvt_pk_bf16_f32 v84, v84, v85
	v_cvt_pk_bf16_f32 v85, v90, v91
	global_store_dwordx4 v[98:99], v[82:85], off offset:256
	s_nop 1
	v_or_b32_e32 v82, 48, v148
	v_ashrrev_i32_e32 v83, 31, v82
	v_lshlrev_b64 v[82:83], 13, v[82:83]
	v_lshl_add_u64 v[82:83], s[20:21], 0, v[82:83]
	v_max_f32_e32 v79, 0, v79
	v_max_f32_e32 v78, 0, v78
	v_max_f32_e32 v81, 0, v81
	v_max_f32_e32 v80, 0, v80
	v_max_f32_e32 v75, 0, v75
	v_max_f32_e32 v74, 0, v74
	v_max_f32_e32 v77, 0, v77
	v_max_f32_e32 v76, 0, v76
	v_lshl_add_u64 v[82:83], v[82:83], 0, v[150:151]
	v_pk_mul_f32 v[80:81], v[80:81], v[80:81]
	v_pk_mul_f32 v[78:79], v[78:79], v[78:79]
	v_pk_mul_f32 v[84:85], v[76:77], v[76:77]
	v_pk_mul_f32 v[76:77], v[74:75], v[74:75]
	v_cvt_pk_bf16_f32 v74, v78, v79
	v_cvt_pk_bf16_f32 v75, v80, v81
	v_max_f32_e32 v67, 0, v67
	v_max_f32_e32 v66, 0, v66
	v_max_f32_e32 v69, 0, v69
	v_max_f32_e32 v68, 0, v68
	v_cvt_pk_bf16_f32 v76, v76, v77
	v_cvt_pk_bf16_f32 v77, v84, v85
	global_store_dwordx4 v[82:83], v[74:77], off
	s_nop 1
	v_max_f32_e32 v71, 0, v71
	v_max_f32_e32 v70, 0, v70
	v_max_f32_e32 v73, 0, v73
	v_max_f32_e32 v72, 0, v72
	v_pk_mul_f32 v[74:75], v[68:69], v[68:69]
	v_pk_mul_f32 v[68:69], v[66:67], v[66:67]
	v_max_f32_e32 v63, 0, v63
; __device__ __forceinline__ unsigned cvt_pk_bf16(float lo, float hi) { unsigned r; asm volatile("v_cvt_pk_bf16_f32 %0, %1, %2" : "=v"(r) : "v"(lo), "v"(hi)); return r; }
; #define PG8_BAR __builtin_amdgcn_s_barrier()
;     __device__ __forceinline__ void operator()(const f32x4 (&acc)[2][2][4][2], const Unit& u, int wr, int wc, int fr, int fq) const {
;     ...
;         for (int ai = 0; ai < 2; ++ai)
; #pragma unroll
;             for (int m = 0; m < 4; ++m) { bf16_t* rowp = O + (size_t)(row0 + ai * HALF + m * 16) * ldc + col0;
; #pragma unroll
;                 for (int bj = 0; bj < 2; ++bj) { f32x4 v0 = acc[ai][bj][m][0], v1 = acc[ai][bj][m][1];
;                     if (ACT == 1) { v0 = __builtin_elementwise_max(v0, (f32x4){0.f, 0.f, 0.f, 0.f}); v1 = __builtin_elementwise_max(v1, (f32x4){0.f, 0.f, 0.f, 0.f}); v0 = v0 * v0; v1 = v1 * v1; }
;                     if (ACT == 2) { v0 = v0 * sv[bj][0]; v1 = v1 * sv[bj][1]; }
;                     u32x4 w; w.x = cvt_pk_bf16(v0[0], v0[1]); w.y = cvt_pk_bf16(v0[2], v0[3]); w.z = cvt_pk_bf16(v1[0], v1[1]); w.w = cvt_pk_bf16(v1[2], v1[3]);
;                     *(u32x4*)(rowp + bj * HALF) = w; } }
; template <class Epi, class Sched, bool ALIGN_EPI = false, bool SP2 = false>
; __device__ __forceinline__ void gemm_phase(PG8_LAS unsigned char* lds, const Gemm g, const Sched& S, const Epi& E) {
;     ...
;         if constexpr (ALIGN_EPI) { if (wr == 0) PG8_BAR; }
;         if constexpr (!Epi::AFTER_DRAIN) { E(acc, cur, wr, wc, fr, fq); S.done(cur); }
;         if (!has_next) break;
; #pragma unroll
;         for (int a = 0; a < 2; ++a)
; #pragma unroll
;             for (int b = 0; b < 2; ++b)
; #pragma unroll
;                 for (int m = 0; m < 4; ++m)
; #pragma unroll
;                     for (int n = 0; n < 2; ++n) acc[a][b][m][n] = (f32x4){0.f, 0.f, 0.f, 0.f};
;         cur = nxt; cA = nA; cB = nB; ++ui;
;         if constexpr (ALIGN_EPI) { if (wr == 1) PG8_BAR; }
;     }
	v_max_f32_e32 v62, 0, v62
	v_pk_mul_f32 v[72:73], v[72:73], v[72:73]
	v_pk_mul_f32 v[70:71], v[70:71], v[70:71]
	v_cvt_pk_bf16_f32 v66, v70, v71
	v_cvt_pk_bf16_f32 v67, v72, v73
	v_cvt_pk_bf16_f32 v68, v68, v69
	v_cvt_pk_bf16_f32 v69, v74, v75
	v_max_f32_e32 v59, 0, v59
	v_max_f32_e32 v58, 0, v58
	v_max_f32_e32 v61, 0, v61
	v_max_f32_e32 v60, 0, v60
	v_pk_mul_f32 v[62:63], v[62:63], v[62:63]
	global_store_dwordx4 v[82:83], v[66:69], off offset:256
	s_nop 1
	v_max_f32_e32 v65, 0, v65
	v_max_f32_e32 v64, 0, v64
	v_pk_mul_f32 v[68:69], v[60:61], v[60:61]
	v_pk_mul_f32 v[60:61], v[58:59], v[58:59]
	v_cvt_pk_bf16_f32 v58, v62, v63
	v_add_co_u32_e32 v62, vcc, s89, v146
	v_pk_mul_f32 v[64:65], v[64:65], v[64:65]
	v_addc_co_u32_e32 v63, vcc, 0, v147, vcc
	v_cvt_pk_bf16_f32 v59, v64, v65
	v_max_f32_e32 v51, 0, v51
	v_max_f32_e32 v50, 0, v50
	v_max_f32_e32 v53, 0, v53
	v_max_f32_e32 v52, 0, v52
	v_cvt_pk_bf16_f32 v60, v60, v61
	v_cvt_pk_bf16_f32 v61, v68, v69
	global_store_dwordx4 v[62:63], v[58:61], off
	s_nop 1
	v_max_f32_e32 v55, 0, v55
	v_max_f32_e32 v54, 0, v54
	v_max_f32_e32 v57, 0, v57
	v_max_f32_e32 v56, 0, v56
	v_pk_mul_f32 v[58:59], v[52:53], v[52:53]
	v_pk_mul_f32 v[52:53], v[50:51], v[50:51]
	v_max_f32_e32 v47, 0, v47
	v_max_f32_e32 v46, 0, v46
	v_lshl_add_u64 v[66:67], v[146:147], 0, s[38:39]
	v_pk_mul_f32 v[56:57], v[56:57], v[56:57]
	v_pk_mul_f32 v[54:55], v[54:55], v[54:55]
	v_cvt_pk_bf16_f32 v50, v54, v55
	v_cvt_pk_bf16_f32 v51, v56, v57
	v_cvt_pk_bf16_f32 v52, v52, v53
	v_cvt_pk_bf16_f32 v53, v58, v59
	v_max_f32_e32 v43, 0, v43
	v_max_f32_e32 v42, 0, v42
	v_max_f32_e32 v45, 0, v45
	v_max_f32_e32 v44, 0, v44
	v_pk_mul_f32 v[46:47], v[46:47], v[46:47]
	global_store_dwordx4 v[66:67], v[50:53], off offset:256
	s_nop 1
	v_max_f32_e32 v49, 0, v49
	v_max_f32_e32 v48, 0, v48
	v_pk_mul_f32 v[52:53], v[44:45], v[44:45]
	v_pk_mul_f32 v[44:45], v[42:43], v[42:43]
	v_cvt_pk_bf16_f32 v42, v46, v47
	v_add_co_u32_e32 v46, vcc, s91, v146
	v_pk_mul_f32 v[48:49], v[48:49], v[48:49]
	v_addc_co_u32_e32 v47, vcc, 0, v147, vcc
	v_cvt_pk_bf16_f32 v43, v48, v49
	v_max_f32_e32 v35, 0, v35
	v_max_f32_e32 v34, 0, v34
	v_max_f32_e32 v37, 0, v37
	v_max_f32_e32 v36, 0, v36
	v_cvt_pk_bf16_f32 v44, v44, v45
	v_cvt_pk_bf16_f32 v45, v52, v53
	global_store_dwordx4 v[46:47], v[42:45], off
	s_nop 1
	v_max_f32_e32 v39, 0, v39
	v_max_f32_e32 v38, 0, v38
	v_max_f32_e32 v41, 0, v41
	v_max_f32_e32 v40, 0, v40
	v_pk_mul_f32 v[42:43], v[36:37], v[36:37]
	v_pk_mul_f32 v[36:37], v[34:35], v[34:35]
	v_max_f32_e32 v31, 0, v31
	v_max_f32_e32 v30, 0, v30
	v_lshl_add_u64 v[50:51], v[146:147], 0, s[40:41]
	v_pk_mul_f32 v[40:41], v[40:41], v[40:41]
	v_pk_mul_f32 v[38:39], v[38:39], v[38:39]
	v_cvt_pk_bf16_f32 v34, v38, v39
	v_cvt_pk_bf16_f32 v35, v40, v41
	v_cvt_pk_bf16_f32 v36, v36, v37
	v_cvt_pk_bf16_f32 v37, v42, v43
	v_max_f32_e32 v27, 0, v27
	v_max_f32_e32 v26, 0, v26
	v_max_f32_e32 v29, 0, v29
	v_max_f32_e32 v28, 0, v28
	v_pk_mul_f32 v[30:31], v[30:31], v[30:31]
	global_store_dwordx4 v[50:51], v[34:37], off offset:256
	s_nop 1
	v_max_f32_e32 v33, 0, v33
	v_max_f32_e32 v32, 0, v32
	v_pk_mul_f32 v[36:37], v[28:29], v[28:29]
	v_pk_mul_f32 v[28:29], v[26:27], v[26:27]
	v_cvt_pk_bf16_f32 v26, v30, v31
	v_add_co_u32_e32 v30, vcc, s92, v146
	v_pk_mul_f32 v[32:33], v[32:33], v[32:33]
	v_addc_co_u32_e32 v31, vcc, 0, v147, vcc
	v_cvt_pk_bf16_f32 v27, v32, v33
	v_max_f32_e32 v19, 0, v19
	v_max_f32_e32 v18, 0, v18
	v_max_f32_e32 v21, 0, v21
	v_max_f32_e32 v20, 0, v20
	v_cvt_pk_bf16_f32 v28, v28, v29
	v_cvt_pk_bf16_f32 v29, v36, v37
	global_store_dwordx4 v[30:31], v[26:29], off
	s_nop 1
	v_max_f32_e32 v23, 0, v23
	v_max_f32_e32 v22, 0, v22
	v_max_f32_e32 v25, 0, v25
	v_max_f32_e32 v24, 0, v24
	v_pk_mul_f32 v[26:27], v[20:21], v[20:21]
	v_pk_mul_f32 v[20:21], v[18:19], v[18:19]
	v_max_f32_e32 v15, 0, v15
	v_max_f32_e32 v14, 0, v14
	v_lshl_add_u64 v[34:35], v[146:147], 0, s[42:43]
	v_pk_mul_f32 v[24:25], v[24:25], v[24:25]
	v_pk_mul_f32 v[22:23], v[22:23], v[22:23]
	v_cvt_pk_bf16_f32 v18, v22, v23
	v_cvt_pk_bf16_f32 v19, v24, v25
	v_cvt_pk_bf16_f32 v20, v20, v21
	v_cvt_pk_bf16_f32 v21, v26, v27
	v_max_f32_e32 v11, 0, v11
	v_max_f32_e32 v10, 0, v10
	v_max_f32_e32 v13, 0, v13
	v_max_f32_e32 v12, 0, v12
	v_pk_mul_f32 v[14:15], v[14:15], v[14:15]
	global_store_dwordx4 v[34:35], v[18:21], off offset:256
	s_nop 1
	v_max_f32_e32 v17, 0, v17
	v_max_f32_e32 v16, 0, v16
	v_pk_mul_f32 v[20:21], v[12:13], v[12:13]
	v_pk_mul_f32 v[12:13], v[10:11], v[10:11]
	v_cvt_pk_bf16_f32 v10, v14, v15
	v_add_co_u32_e32 v14, vcc, s93, v146
	v_pk_mul_f32 v[16:17], v[16:17], v[16:17]
	v_addc_co_u32_e32 v15, vcc, 0, v147, vcc
	v_cvt_pk_bf16_f32 v11, v16, v17
	v_max_f32_e32 v3, 0, v3
	v_max_f32_e32 v2, 0, v2
	v_max_f32_e32 v5, 0, v5
	v_max_f32_e32 v4, 0, v4
	v_lshl_add_u64 v[18:19], v[146:147], 0, s[44:45]
	v_cvt_pk_bf16_f32 v12, v12, v13
	v_cvt_pk_bf16_f32 v13, v20, v21
	global_store_dwordx4 v[14:15], v[10:13], off
	s_nop 1
	v_max_f32_e32 v7, 0, v7
	v_max_f32_e32 v6, 0, v6
	v_max_f32_e32 v9, 0, v9
	v_max_f32_e32 v8, 0, v8
	v_pk_mul_f32 v[10:11], v[4:5], v[4:5]
	v_pk_mul_f32 v[4:5], v[2:3], v[2:3]
	s_and_b64 vcc, exec, s[2:3]
	s_mov_b64 s[0:1], -1
	v_pk_mul_f32 v[8:9], v[8:9], v[8:9]
	v_pk_mul_f32 v[6:7], v[6:7], v[6:7]
	s_nop 0
	v_cvt_pk_bf16_f32 v2, v6, v7
	v_cvt_pk_bf16_f32 v3, v8, v9
	v_cvt_pk_bf16_f32 v4, v4, v5
	v_cvt_pk_bf16_f32 v5, v10, v11
	global_store_dwordx4 v[18:19], v[2:5], off offset:256
	s_nop 1
	s_cbranch_vccnz .LBB0_372
	s_andn2_b64 vcc, exec, s[6:7]
	s_cbranch_vccnz .LBB0_371
	s_barrier
	s_branch .LBB0_371
